# blocked H layout + P5 epilogue with all residual loads issued up front
# speedup vs baseline: 1.0013x; 1.0013x over previous
; #define PG8_STAGE(bufoff, gbase, voff) do { _Pragma("unroll") for (int _i = 0; _i < 2; ++_i) \
;         __builtin_amdgcn_global_load_lds((const unsigned*)((const char*)(gbase) + (voff)[_i]), (PG8_LAS unsigned*)(lds + (bufoff) + ldsw + _i * 8192), 16, 0, 0); } while (0)
; #define PG8_LDA(dst, b, h) do { _Pragma("unroll") for (int m = 0; m < 4; ++m) _Pragma("unroll") for (int k = 0; k < 2; ++k) dst[m][k] = *(const PG8_LAS bf16x8*)(lds + PG8_SA(b, h) + aoff + m * 2048 + k * 1024); } while (0)
; #define PG8_LDB(dst, b, h) do { _Pragma("unroll") for (int n = 0; n < 2; ++n) _Pragma("unroll") for (int k = 0; k < 2; ++k) dst[n][k] = *(const PG8_LAS bf16x8*)(lds + PG8_SB(b, h) + boff + n * 2048 + k * 1024); } while (0)
; #define PG8_MMA(ai, bj, At, Bt) do { __builtin_amdgcn_s_setprio(1); _Pragma("unroll") for (int m = 0; m < 4; ++m) _Pragma("unroll") for (int n = 0; n < 2; ++n) _Pragma("unroll") for (int k = 0; k < 2; ++k) \
;         acc[ai][bj][m][n] = __builtin_amdgcn_mfma_f32_16x16x32_bf16(Bt[n][k], At[m][k], acc[ai][bj][m][n], 0, 0, 0); __builtin_amdgcn_s_setprio(0); } while (0)
; #define PG8_WAIT_V(n) asm volatile("s_waitcnt vmcnt(" #n ")" ::: "memory")
; #define PG8_WAIT_L(n) asm volatile("s_waitcnt lgkmcnt(" #n ")" ::: "memory")
; #define PG8_BAR __builtin_amdgcn_s_barrier()
; #define PG8_SCHED __builtin_amdgcn_sched_barrier(0)
; template <class Epi, class Sched, bool ALIGN_EPI = false, bool SP2 = false>
; __device__ __forceinline__ void gemm_phase(PG8_LAS unsigned char* lds, const Gemm g, const Sched& S, const Epi& E) {
;     ...
;             PG8_LDB(B0, 0, 0); PG8_LDB(B1, 0, 1); PG8_SCHED; PG8_LDA(At, 0, 0); PG8_STAGE(PG8_SA(1, 1), a1 + hstep, voffA);
;             PG8_WAIT_V(8); PG8_WAIT_L(0); PG8_BAR; PG8_MMA(0, 0, At, B0); PG8_MMA(0, 1, At, B1); PG8_BAR; PG8_SCHED;
;             PG8_LDA(At, 0, 1); PG8_STAGE(PG8_SB(0, 0), b2, voffB); PG8_STAGE(PG8_SB(0, 1), b2 + hstep, voffB); PG8_STAGE(PG8_SA(0, 0), a2, voffA);
;             PG8_WAIT_V(8); PG8_WAIT_L(0); PG8_BAR; PG8_MMA(1, 0, At, B0); PG8_MMA(1, 1, At, B1); PG8_BAR; PG8_SCHED;
.LBB0_1498:
	ds_read_b128 v[142:145], v148
	ds_read_b128 v[154:157], v148 offset:1024
	ds_read_b128 v[158:161], v148 offset:2048
	ds_read_b128 v[162:165], v148 offset:3072
	ds_read_b128 v[166:169], v149
	ds_read_b128 v[170:173], v149 offset:1024
	ds_read_b128 v[174:177], v149 offset:2048
	ds_read_b128 v[178:181], v149 offset:3072
	s_add_u32 s24, s22, 0x4000
	s_addc_u32 s25, s23, 0
	s_cmp_eq_u32 s47, 60
	s_cselect_b32 s27, s11, s25
	s_cselect_b32 s26, s43, s24
	s_cselect_b32 s25, s9, s46
	s_cselect_b32 s24, s44, s45
	v_lshl_add_u64 v[214:215], s[22:23], 0, v[136:137]
	s_add_i32 m0, s19, 0xc000
	ds_read_b128 v[182:185], v150
	ds_read_b128 v[186:189], v150 offset:1024
	ds_read_b128 v[190:193], v150 offset:2048
	ds_read_b128 v[194:197], v150 offset:3072
	ds_read_b128 v[198:201], v150 offset:4096
	ds_read_b128 v[202:205], v150 offset:5120
	ds_read_b128 v[206:209], v150 offset:6144
	ds_read_b128 v[210:213], v150 offset:7168
	global_load_lds_dwordx4 v[214:215], off
	v_lshl_add_u64 v[214:215], s[22:23], 0, v[138:139]
	s_add_i32 m0, s19, 0xe000
	s_nop 0
	global_load_lds_dwordx4 v[214:215], off
	s_waitcnt vmcnt(8)
	s_waitcnt lgkmcnt(0)
	s_barrier
	s_setprio 1
	s_waitcnt lgkmcnt(0)
	v_mfma_f32_16x16x32_bf16 v[124:127], v[142:145], v[182:185], v[124:127]
	v_mfma_f32_16x16x32_bf16 v[120:123], v[158:161], v[182:185], v[120:123]
	v_mfma_f32_16x16x32_bf16 v[108:111], v[142:145], v[190:193], v[108:111]
	v_mfma_f32_16x16x32_bf16 v[104:107], v[158:161], v[190:193], v[104:107]
	v_mfma_f32_16x16x32_bf16 v[92:95], v[142:145], v[198:201], v[92:95]
	v_mfma_f32_16x16x32_bf16 v[88:91], v[158:161], v[198:201], v[88:91]
	v_mfma_f32_16x16x32_bf16 v[76:79], v[142:145], v[206:209], v[76:79]
	v_mfma_f32_16x16x32_bf16 v[72:75], v[158:161], v[206:209], v[72:75]
	v_mfma_f32_16x16x32_bf16 v[124:127], v[154:157], v[186:189], v[124:127]
	v_mfma_f32_16x16x32_bf16 v[120:123], v[162:165], v[186:189], v[120:123]
	v_mfma_f32_16x16x32_bf16 v[108:111], v[154:157], v[194:197], v[108:111]
	v_mfma_f32_16x16x32_bf16 v[104:107], v[162:165], v[194:197], v[104:107]
	v_mfma_f32_16x16x32_bf16 v[92:95], v[154:157], v[202:205], v[92:95]
	v_mfma_f32_16x16x32_bf16 v[88:91], v[162:165], v[202:205], v[88:91]
	v_mfma_f32_16x16x32_bf16 v[76:79], v[154:157], v[210:213], v[76:79]
	v_mfma_f32_16x16x32_bf16 v[72:75], v[162:165], v[210:213], v[72:75]
	s_setprio 0
	s_setprio 1
	v_mfma_f32_16x16x32_bf16 v[116:119], v[166:169], v[182:185], v[116:119]
	v_mfma_f32_16x16x32_bf16 v[112:115], v[174:177], v[182:185], v[112:115]
	v_mfma_f32_16x16x32_bf16 v[100:103], v[166:169], v[190:193], v[100:103]
	v_mfma_f32_16x16x32_bf16 v[96:99], v[174:177], v[190:193], v[96:99]
	v_mfma_f32_16x16x32_bf16 v[84:87], v[166:169], v[198:201], v[84:87]
	v_mfma_f32_16x16x32_bf16 v[80:83], v[174:177], v[198:201], v[80:83]
	v_mfma_f32_16x16x32_bf16 v[68:71], v[166:169], v[206:209], v[68:71]
	v_mfma_f32_16x16x32_bf16 v[64:67], v[174:177], v[206:209], v[64:67]
	v_mfma_f32_16x16x32_bf16 v[116:119], v[170:173], v[186:189], v[116:119]
	v_mfma_f32_16x16x32_bf16 v[112:115], v[178:181], v[186:189], v[112:115]
	v_mfma_f32_16x16x32_bf16 v[100:103], v[170:173], v[194:197], v[100:103]
	v_mfma_f32_16x16x32_bf16 v[96:99], v[178:181], v[194:197], v[96:99]
	v_mfma_f32_16x16x32_bf16 v[84:87], v[170:173], v[202:205], v[84:87]
	v_mfma_f32_16x16x32_bf16 v[80:83], v[178:181], v[202:205], v[80:83]
	v_mfma_f32_16x16x32_bf16 v[68:71], v[170:173], v[210:213], v[68:71]
	v_mfma_f32_16x16x32_bf16 v[64:67], v[178:181], v[210:213], v[64:67]
	s_setprio 0
	s_barrier
	s_add_i32 s48, s37, s29
	v_lshl_add_u64 v[214:215], s[24:25], 0, v[130:131]
	s_mov_b32 m0, s48
	ds_read_b128 v[182:185], v150 offset:16384
	ds_read_b128 v[186:189], v150 offset:17408
	ds_read_b128 v[190:193], v150 offset:18432
	ds_read_b128 v[194:197], v150 offset:19456
	ds_read_b128 v[198:201], v150 offset:20480
	ds_read_b128 v[202:205], v150 offset:21504
	ds_read_b128 v[206:209], v150 offset:22528
	ds_read_b128 v[210:213], v150 offset:23552
	global_load_lds_dwordx4 v[214:215], off
	s_add_i32 m0, s48, 0x2000
	s_add_u32 s48, s24, 0x100000
	v_lshl_add_u64 v[216:217], s[24:25], 0, v[134:135]
	s_addc_u32 s49, s25, 0
	s_add_i32 s52, s38, s29
	global_load_lds_dwordx4 v[216:217], off
	v_lshl_add_u64 v[218:219], s[48:49], 0, v[130:131]
	s_mov_b32 m0, s52
	v_lshl_add_u64 v[220:221], s[26:27], 0, v[132:133]
	global_load_lds_dwordx4 v[218:219], off
	v_lshl_add_u64 v[218:219], s[48:49], 0, v[134:135]
	s_add_i32 m0, s52, 0x2000
	s_nop 0
	global_load_lds_dwordx4 v[218:219], off
	v_lshl_add_u64 v[218:219], s[26:27], 0, v[128:129]
	s_mov_b32 m0, s19
	s_nop 0
	global_load_lds_dwordx4 v[218:219], off
	s_mov_b32 m0, s21
	s_nop 0
	global_load_lds_dwordx4 v[220:221], off
	s_waitcnt vmcnt(8)
	s_waitcnt lgkmcnt(0)
	s_barrier
; #define PG8_STAGE(bufoff, gbase, voff) do { _Pragma("unroll") for (int _i = 0; _i < 2; ++_i) \
;         __builtin_amdgcn_global_load_lds((const unsigned*)((const char*)(gbase) + (voff)[_i]), (PG8_LAS unsigned*)(lds + (bufoff) + ldsw + _i * 8192), 16, 0, 0); } while (0)
; #define PG8_LDA(dst, b, h) do { _Pragma("unroll") for (int m = 0; m < 4; ++m) _Pragma("unroll") for (int k = 0; k < 2; ++k) dst[m][k] = *(const PG8_LAS bf16x8*)(lds + PG8_SA(b, h) + aoff + m * 2048 + k * 1024); } while (0)
; #define PG8_LDB(dst, b, h) do { _Pragma("unroll") for (int n = 0; n < 2; ++n) _Pragma("unroll") for (int k = 0; k < 2; ++k) dst[n][k] = *(const PG8_LAS bf16x8*)(lds + PG8_SB(b, h) + boff + n * 2048 + k * 1024); } while (0)
; #define PG8_MMA(ai, bj, At, Bt) do { __builtin_amdgcn_s_setprio(1); _Pragma("unroll") for (int m = 0; m < 4; ++m) _Pragma("unroll") for (int n = 0; n < 2; ++n) _Pragma("unroll") for (int k = 0; k < 2; ++k) \
;         acc[ai][bj][m][n] = __builtin_amdgcn_mfma_f32_16x16x32_bf16(Bt[n][k], At[m][k], acc[ai][bj][m][n], 0, 0, 0); __builtin_amdgcn_s_setprio(0); } while (0)
; #define PG8_WAIT_V(n) asm volatile("s_waitcnt vmcnt(" #n ")" ::: "memory")
; #define PG8_WAIT_L(n) asm volatile("s_waitcnt lgkmcnt(" #n ")" ::: "memory")
; #define PG8_BAR __builtin_amdgcn_s_barrier()
; #define PG8_SCHED __builtin_amdgcn_sched_barrier(0)
; template <class Epi, class Sched, bool ALIGN_EPI = false, bool SP2 = false>
; __device__ __forceinline__ void gemm_phase(PG8_LAS unsigned char* lds, const Gemm g, const Sched& S, const Epi& E) {
;     ...
;             PG8_WAIT_V(8); PG8_WAIT_L(0); PG8_BAR; PG8_MMA(1, 0, At, B0); PG8_MMA(1, 1, At, B1); PG8_BAR; PG8_SCHED;
;             PG8_LDB(B0, 1, 0); PG8_LDB(B1, 1, 1); PG8_SCHED; PG8_LDA(At, 1, 0); PG8_STAGE(PG8_SA(0, 1), a2 + hstep, voffA);
;             PG8_WAIT_V(8); PG8_WAIT_L(0); PG8_BAR; PG8_MMA(0, 0, At, B0); PG8_MMA(0, 1, At, B1); PG8_BAR; PG8_SCHED;
	s_setprio 1
	s_waitcnt lgkmcnt(0)
	v_mfma_f32_16x16x32_bf16 v[60:63], v[142:145], v[182:185], v[60:63]
	v_mfma_f32_16x16x32_bf16 v[56:59], v[158:161], v[182:185], v[56:59]
	v_mfma_f32_16x16x32_bf16 v[44:47], v[142:145], v[190:193], v[44:47]
	v_mfma_f32_16x16x32_bf16 v[40:43], v[158:161], v[190:193], v[40:43]
	v_mfma_f32_16x16x32_bf16 v[28:31], v[142:145], v[198:201], v[28:31]
	v_mfma_f32_16x16x32_bf16 v[24:27], v[158:161], v[198:201], v[24:27]
	v_mfma_f32_16x16x32_bf16 v[12:15], v[142:145], v[206:209], v[12:15]
	v_mfma_f32_16x16x32_bf16 v[8:11], v[158:161], v[206:209], v[8:11]
	v_mfma_f32_16x16x32_bf16 v[60:63], v[154:157], v[186:189], v[60:63]
	v_mfma_f32_16x16x32_bf16 v[56:59], v[162:165], v[186:189], v[56:59]
	v_mfma_f32_16x16x32_bf16 v[44:47], v[154:157], v[194:197], v[44:47]
	v_mfma_f32_16x16x32_bf16 v[40:43], v[162:165], v[194:197], v[40:43]
	v_mfma_f32_16x16x32_bf16 v[28:31], v[154:157], v[202:205], v[28:31]
	v_mfma_f32_16x16x32_bf16 v[24:27], v[162:165], v[202:205], v[24:27]
	v_mfma_f32_16x16x32_bf16 v[12:15], v[154:157], v[210:213], v[12:15]
	v_mfma_f32_16x16x32_bf16 v[8:11], v[162:165], v[210:213], v[8:11]
	s_setprio 0
	s_setprio 1
	v_mfma_f32_16x16x32_bf16 v[52:55], v[166:169], v[182:185], v[52:55]
	v_mfma_f32_16x16x32_bf16 v[48:51], v[174:177], v[182:185], v[48:51]
	v_mfma_f32_16x16x32_bf16 v[36:39], v[166:169], v[190:193], v[36:39]
	v_mfma_f32_16x16x32_bf16 v[32:35], v[174:177], v[190:193], v[32:35]
	v_mfma_f32_16x16x32_bf16 v[20:23], v[166:169], v[198:201], v[20:23]
	v_mfma_f32_16x16x32_bf16 v[16:19], v[174:177], v[198:201], v[16:19]
	v_mfma_f32_16x16x32_bf16 v[4:7], v[166:169], v[206:209], v[4:7]
	v_mfma_f32_16x16x32_bf16 v[0:3], v[174:177], v[206:209], v[0:3]
	v_mfma_f32_16x16x32_bf16 v[52:55], v[170:173], v[186:189], v[52:55]
	v_mfma_f32_16x16x32_bf16 v[48:51], v[178:181], v[186:189], v[48:51]
	v_mfma_f32_16x16x32_bf16 v[36:39], v[170:173], v[194:197], v[36:39]
	v_mfma_f32_16x16x32_bf16 v[32:35], v[178:181], v[194:197], v[32:35]
	v_mfma_f32_16x16x32_bf16 v[20:23], v[170:173], v[202:205], v[20:23]
	v_mfma_f32_16x16x32_bf16 v[16:19], v[178:181], v[202:205], v[16:19]
	v_mfma_f32_16x16x32_bf16 v[4:7], v[170:173], v[210:213], v[4:7]
	v_mfma_f32_16x16x32_bf16 v[0:3], v[178:181], v[210:213], v[0:3]
	s_setprio 0
	s_barrier
	ds_read_b128 v[142:145], v151
	ds_read_b128 v[154:157], v151 offset:1024
	ds_read_b128 v[158:161], v151 offset:2048
	ds_read_b128 v[162:165], v151 offset:3072
	ds_read_b128 v[166:169], v152
	ds_read_b128 v[170:173], v152 offset:1024
	ds_read_b128 v[174:177], v152 offset:2048
	ds_read_b128 v[178:181], v152 offset:3072
	s_add_u32 s26, s26, 0x4000
	s_addc_u32 s27, s27, 0
	s_mov_b32 m0, s31
	v_lshl_add_u64 v[222:223], s[26:27], 0, v[128:129]
	ds_read_b128 v[182:185], v150 offset:32768
	ds_read_b128 v[186:189], v150 offset:33792
	ds_read_b128 v[190:193], v150 offset:34816
	ds_read_b128 v[194:197], v150 offset:35840
	ds_read_b128 v[198:201], v150 offset:36864
	ds_read_b128 v[202:205], v150 offset:37888
	ds_read_b128 v[206:209], v150 offset:38912
	ds_read_b128 v[210:213], v150 offset:39936
	global_load_lds_dwordx4 v[222:223], off
	v_lshl_add_u64 v[222:223], s[26:27], 0, v[132:133]
	s_mov_b32 m0, s33
	s_nop 0
	global_load_lds_dwordx4 v[222:223], off
	s_waitcnt vmcnt(8)
	s_waitcnt lgkmcnt(0)
	s_barrier
	s_setprio 1
	s_waitcnt lgkmcnt(0)
	v_mfma_f32_16x16x32_bf16 v[124:127], v[142:145], v[182:185], v[124:127]
	v_mfma_f32_16x16x32_bf16 v[120:123], v[158:161], v[182:185], v[120:123]
	v_mfma_f32_16x16x32_bf16 v[108:111], v[142:145], v[190:193], v[108:111]
	v_mfma_f32_16x16x32_bf16 v[104:107], v[158:161], v[190:193], v[104:107]
	v_mfma_f32_16x16x32_bf16 v[92:95], v[142:145], v[198:201], v[92:95]
	v_mfma_f32_16x16x32_bf16 v[88:91], v[158:161], v[198:201], v[88:91]
	v_mfma_f32_16x16x32_bf16 v[76:79], v[142:145], v[206:209], v[76:79]
	v_mfma_f32_16x16x32_bf16 v[72:75], v[158:161], v[206:209], v[72:75]
	v_mfma_f32_16x16x32_bf16 v[124:127], v[154:157], v[186:189], v[124:127]
	v_mfma_f32_16x16x32_bf16 v[120:123], v[162:165], v[186:189], v[120:123]
	v_mfma_f32_16x16x32_bf16 v[108:111], v[154:157], v[194:197], v[108:111]
	v_mfma_f32_16x16x32_bf16 v[104:107], v[162:165], v[194:197], v[104:107]
	v_mfma_f32_16x16x32_bf16 v[92:95], v[154:157], v[202:205], v[92:95]
	v_mfma_f32_16x16x32_bf16 v[88:91], v[162:165], v[202:205], v[88:91]
	v_mfma_f32_16x16x32_bf16 v[76:79], v[154:157], v[210:213], v[76:79]
	v_mfma_f32_16x16x32_bf16 v[72:75], v[162:165], v[210:213], v[72:75]
	s_setprio 0
	s_setprio 1
	v_mfma_f32_16x16x32_bf16 v[116:119], v[166:169], v[182:185], v[116:119]
	v_mfma_f32_16x16x32_bf16 v[112:115], v[174:177], v[182:185], v[112:115]
	v_mfma_f32_16x16x32_bf16 v[100:103], v[166:169], v[190:193], v[100:103]
	v_mfma_f32_16x16x32_bf16 v[96:99], v[174:177], v[190:193], v[96:99]
	v_mfma_f32_16x16x32_bf16 v[84:87], v[166:169], v[198:201], v[84:87]
	v_mfma_f32_16x16x32_bf16 v[80:83], v[174:177], v[198:201], v[80:83]
	v_mfma_f32_16x16x32_bf16 v[68:71], v[166:169], v[206:209], v[68:71]
	v_mfma_f32_16x16x32_bf16 v[64:67], v[174:177], v[206:209], v[64:67]
	v_mfma_f32_16x16x32_bf16 v[116:119], v[170:173], v[186:189], v[116:119]
	v_mfma_f32_16x16x32_bf16 v[112:115], v[178:181], v[186:189], v[112:115]
	v_mfma_f32_16x16x32_bf16 v[100:103], v[170:173], v[194:197], v[100:103]
	v_mfma_f32_16x16x32_bf16 v[96:99], v[178:181], v[194:197], v[96:99]
	v_mfma_f32_16x16x32_bf16 v[84:87], v[170:173], v[202:205], v[84:87]
	v_mfma_f32_16x16x32_bf16 v[80:83], v[178:181], v[202:205], v[80:83]
	v_mfma_f32_16x16x32_bf16 v[68:71], v[170:173], v[210:213], v[68:71]
	v_mfma_f32_16x16x32_bf16 v[64:67], v[178:181], v[210:213], v[64:67]
	s_setprio 0
	s_barrier
; #define PG8_STAGE(bufoff, gbase, voff) do { _Pragma("unroll") for (int _i = 0; _i < 2; ++_i) \
;         __builtin_amdgcn_global_load_lds((const unsigned*)((const char*)(gbase) + (voff)[_i]), (PG8_LAS unsigned*)(lds + (bufoff) + ldsw + _i * 8192), 16, 0, 0); } while (0)
; #define PG8_LDA(dst, b, h) do { _Pragma("unroll") for (int m = 0; m < 4; ++m) _Pragma("unroll") for (int k = 0; k < 2; ++k) dst[m][k] = *(const PG8_LAS bf16x8*)(lds + PG8_SA(b, h) + aoff + m * 2048 + k * 1024); } while (0)
; #define PG8_MMA(ai, bj, At, Bt) do { __builtin_amdgcn_s_setprio(1); _Pragma("unroll") for (int m = 0; m < 4; ++m) _Pragma("unroll") for (int n = 0; n < 2; ++n) _Pragma("unroll") for (int k = 0; k < 2; ++k) \
;         acc[ai][bj][m][n] = __builtin_amdgcn_mfma_f32_16x16x32_bf16(Bt[n][k], At[m][k], acc[ai][bj][m][n], 0, 0, 0); __builtin_amdgcn_s_setprio(0); } while (0)
; #define PG8_WAIT_V(n) asm volatile("s_waitcnt vmcnt(" #n ")" ::: "memory")
; #define PG8_WAIT_L(n) asm volatile("s_waitcnt lgkmcnt(" #n ")" ::: "memory")
; #define PG8_BAR __builtin_amdgcn_s_barrier()
; #define PG8_SCHED __builtin_amdgcn_sched_barrier(0)
;     __device__ __forceinline__ void operator()(const f32x4 (&acc)[2][2][4][2], const Unit& u, int wr, int wc, int fr, int fq) const {
;         const int col0 = u.pn * BM + wc * 32 + 8 * fq;
; #pragma unroll
;         for (int ai = 0; ai < 2; ++ai)
; #pragma unroll
;             for (int m = 0; m < 4; ++m) { const int r = u.pm * BM + ai * HALF + wr * 64 + m * 16 + fr; const size_t off = (size_t)r * 1024 + col0;
; #pragma unroll
;                 for (int bj = 0; bj < 2; ++bj) { const u32x4 w = __builtin_nontemporal_load((const u32x4*)(xb + off + bj * HALF));
; template <class Epi, class Sched, bool ALIGN_EPI = false, bool SP2 = false>
; __device__ __forceinline__ void gemm_phase(PG8_LAS unsigned char* lds, const Gemm g, const Sched& S, const Epi& E) {
;     ...
;             PG8_LDA(At, 1, 1); PG8_STAGE(PG8_SB(1, 0), b3, voffB); PG8_STAGE(PG8_SB(1, 1), b3 + hstep, voffB); PG8_STAGE(PG8_SA(1, 0), a3, voffA);
;             PG8_WAIT_V(8); PG8_WAIT_L(0); PG8_BAR; PG8_MMA(1, 0, At, B0); PG8_MMA(1, 1, At, B1); PG8_BAR; PG8_SCHED;
	s_add_i32 s26, s39, s29
	v_lshl_add_u64 v[214:215], v[214:215], 0, s[4:5]
	s_mov_b32 m0, s26
	ds_read_b128 v[182:185], v150 offset:49152
	ds_read_b128 v[186:189], v150 offset:50176
	ds_read_b128 v[190:193], v150 offset:51200
	ds_read_b128 v[194:197], v150 offset:52224
	ds_read_b128 v[198:201], v150 offset:53248
	ds_read_b128 v[202:205], v150 offset:54272
	ds_read_b128 v[206:209], v150 offset:55296
	ds_read_b128 v[210:213], v150 offset:56320
	global_load_lds_dwordx4 v[214:215], off
	s_add_i32 m0, s26, 0x2000
	s_add_u32 s24, s24, 0x100080
	v_lshl_add_u64 v[214:215], v[216:217], 0, s[4:5]
	s_addc_u32 s25, s25, 0
	s_add_i32 s26, s40, s29
	global_load_lds_dwordx4 v[214:215], off
	v_lshl_add_u64 v[214:215], s[24:25], 0, v[130:131]
	s_mov_b32 m0, s26
	s_nop 0
	global_load_lds_dwordx4 v[214:215], off
	v_lshl_add_u64 v[214:215], s[24:25], 0, v[134:135]
	s_add_i32 m0, s26, 0x2000
	s_nop 0
	global_load_lds_dwordx4 v[214:215], off
	v_lshl_add_u64 v[214:215], v[218:219], 0, s[70:71]
	s_mov_b32 m0, s34
	s_nop 0
	global_load_lds_dwordx4 v[214:215], off
	v_lshl_add_u64 v[214:215], v[220:221], 0, s[70:71]
	s_mov_b32 m0, s35
	s_nop 0
	global_load_lds_dwordx4 v[214:215], off
	s_waitcnt vmcnt(8)
	s_waitcnt lgkmcnt(0)
	s_barrier
	s_setprio 1
	s_waitcnt lgkmcnt(0)
	v_mfma_f32_16x16x32_bf16 v[60:63], v[142:145], v[182:185], v[60:63]
	v_mfma_f32_16x16x32_bf16 v[56:59], v[158:161], v[182:185], v[56:59]
	v_mfma_f32_16x16x32_bf16 v[44:47], v[142:145], v[190:193], v[44:47]
	v_mfma_f32_16x16x32_bf16 v[40:43], v[158:161], v[190:193], v[40:43]
	v_mfma_f32_16x16x32_bf16 v[28:31], v[142:145], v[198:201], v[28:31]
	v_mfma_f32_16x16x32_bf16 v[24:27], v[158:161], v[198:201], v[24:27]
	v_mfma_f32_16x16x32_bf16 v[12:15], v[142:145], v[206:209], v[12:15]
	v_mfma_f32_16x16x32_bf16 v[8:11], v[158:161], v[206:209], v[8:11]
	v_mfma_f32_16x16x32_bf16 v[60:63], v[154:157], v[186:189], v[60:63]
	v_mfma_f32_16x16x32_bf16 v[56:59], v[162:165], v[186:189], v[56:59]
	v_mfma_f32_16x16x32_bf16 v[44:47], v[154:157], v[194:197], v[44:47]
	v_mfma_f32_16x16x32_bf16 v[40:43], v[162:165], v[194:197], v[40:43]
	v_mfma_f32_16x16x32_bf16 v[28:31], v[154:157], v[202:205], v[28:31]
	v_mfma_f32_16x16x32_bf16 v[24:27], v[162:165], v[202:205], v[24:27]
	v_mfma_f32_16x16x32_bf16 v[12:15], v[154:157], v[210:213], v[12:15]
	v_mfma_f32_16x16x32_bf16 v[8:11], v[162:165], v[210:213], v[8:11]
	s_setprio 0
	s_setprio 1
	v_mfma_f32_16x16x32_bf16 v[52:55], v[166:169], v[182:185], v[52:55]
	v_mfma_f32_16x16x32_bf16 v[48:51], v[174:177], v[182:185], v[48:51]
	v_mfma_f32_16x16x32_bf16 v[36:39], v[166:169], v[190:193], v[36:39]
	v_mfma_f32_16x16x32_bf16 v[32:35], v[174:177], v[190:193], v[32:35]
	v_mfma_f32_16x16x32_bf16 v[20:23], v[166:169], v[198:201], v[20:23]
	v_mfma_f32_16x16x32_bf16 v[16:19], v[174:177], v[198:201], v[16:19]
	v_mfma_f32_16x16x32_bf16 v[4:7], v[166:169], v[206:209], v[4:7]
	v_mfma_f32_16x16x32_bf16 v[0:3], v[174:177], v[206:209], v[0:3]
	v_mfma_f32_16x16x32_bf16 v[52:55], v[170:173], v[186:189], v[52:55]
	v_mfma_f32_16x16x32_bf16 v[48:51], v[178:181], v[186:189], v[48:51]
	v_mfma_f32_16x16x32_bf16 v[36:39], v[170:173], v[194:197], v[36:39]
	v_mfma_f32_16x16x32_bf16 v[32:35], v[178:181], v[194:197], v[32:35]
	v_mfma_f32_16x16x32_bf16 v[20:23], v[170:173], v[202:205], v[20:23]
	v_mfma_f32_16x16x32_bf16 v[16:19], v[178:181], v[202:205], v[16:19]
	v_mfma_f32_16x16x32_bf16 v[4:7], v[170:173], v[210:213], v[4:7]
	v_mfma_f32_16x16x32_bf16 v[0:3], v[178:181], v[210:213], v[0:3]
	s_setprio 0
	s_barrier
	s_add_i32 s47, s47, 2
	s_add_u32 s22, s22, 0x10000
	s_addc_u32 s23, s23, 0
	s_add_u32 s45, s45, 0x100
	s_addc_u32 s46, s46, 0
	s_cmp_gt_u32 s47, 61
	s_cbranch_scc0 .LBB0_1498
	v_lshl_add_u32 v144, s20, 8, v146
	v_lshl_or_b32 v142, s18, 8, v147
	v_ashrrev_i32_e32 v145, 31, v144
	v_ashrrev_i32_e32 v143, 31, v142
	v_lshlrev_b64 v[228:229], 10, v[144:145]
	v_lshl_add_u64 v[228:229], v[228:229], 0, v[142:143]
	v_lshl_add_u64 v[236:237], v[228:229], 1, s[66:67]
	v_lshl_add_u64 v[238:239], v[228:229], 2, s[60:61]
	s_mov_b64 s[70:71], 0x8000
	s_mov_b64 s[72:73], 0x28000
	s_mov_b64 s[74:75], 0x10000
	s_mov_b64 s[76:77], 0x50000
	global_load_dwordx4 v[154:157], v[236:237], off nt
	global_load_dwordx4 v[158:161], v[236:237], off offset:256 nt
	v_lshl_add_u64 v[236:237], v[236:237], 0, s[70:71]
	global_load_dwordx4 v[162:165], v[236:237], off nt
	global_load_dwordx4 v[166:169], v[236:237], off offset:256 nt
	v_lshl_add_u64 v[236:237], v[236:237], 0, s[70:71]
	global_load_dwordx4 v[170:173], v[236:237], off nt
	global_load_dwordx4 v[174:177], v[236:237], off offset:256 nt
	v_lshl_add_u64 v[236:237], v[236:237], 0, s[70:71]
	global_load_dwordx4 v[178:181], v[236:237], off nt
	global_load_dwordx4 v[182:185], v[236:237], off offset:256 nt
	v_lshl_add_u64 v[236:237], v[236:237], 0, s[72:73]
	global_load_dwordx4 v[186:189], v[236:237], off nt
	global_load_dwordx4 v[190:193], v[236:237], off offset:256 nt
	v_lshl_add_u64 v[236:237], v[236:237], 0, s[70:71]
	global_load_dwordx4 v[194:197], v[236:237], off nt
	global_load_dwordx4 v[198:201], v[236:237], off offset:256 nt
	v_lshl_add_u64 v[236:237], v[236:237], 0, s[70:71]
	global_load_dwordx4 v[202:205], v[236:237], off nt
	global_load_dwordx4 v[206:209], v[236:237], off offset:256 nt
	v_lshl_add_u64 v[236:237], v[236:237], 0, s[70:71]
	global_load_dwordx4 v[210:213], v[236:237], off nt
	global_load_dwordx4 v[224:227], v[236:237], off offset:256 nt
	s_and_b64 vcc, exec, s[6:7]
	s_cbranch_vccz .LBB0_1501
	s_barrier
